# v92 with the rope epilogue math re-emitted: packed mul/add, sign and lane selection done with two exec masks (12 fewer VALU per row group on the in-proj critical path), bit-identical arithmetic
# speedup vs baseline: 1.0127x; 1.0042x over previous
; __device__ __forceinline__ u32x4 pack8(const float (&v)[8]) { u32x4 w; w.x = pk2(v[0], v[1]); w.y = pk2(v[2], v[3]); w.z = pk2(v[4], v[5]); w.w = pk2(v[6], v[7]); return w; }
;     __device__ __forceinline__ bool operator()(Acc& acc, const Unit& u, int wr, int wc, int fr, int fq, const LAS float* rstab) const {
;     ...
;                 if (rope) {
;                     const float sgn = (fq == 0) ? -1.f : 1.f;
; #pragma unroll
;                     for (int ai = 0; ai < 2; ++ai)
; #pragma unroll
;                         for (int m = 0; m < 4; ++m) {
;                             const float rs = rsp[ai * HALF + m * 16] * scale;
;                             const int pos = (rowb + ai * HALF + m * 16) & (SEQ - 1);
;                             const f32x4 c0 = gld<f32x4>(ropec + pos * 8), c1 = gld<f32x4>(ropec + pos * 8 + 4);
;                             const f32x4 s0 = gld<f32x4>(ropes + pos * 8), s1 = gld<f32x4>(ropes + pos * 8 + 4);
;                             float v[8];
; #pragma unroll
;                             for (int e = 0; e < 4; ++e) { v[e] = acc[ai][bj][m][0][e] * rs; v[4 + e] = acc[ai][bj][m][1][e] * rs; }
; #pragma unroll
;                             for (int e = 0; e < 8; ++e) {
;                                 const float p = __shfl_xor(v[e], 16);
;                                 const float cs = e < 4 ? c0[e & 3] : c1[e & 3], sn = e < 4 ? s0[e & 3] : s1[e & 3];
;                                 const float r = v[e] * cs + sgn * p * sn;
;                                 v[e] = (fq < 2) ? r : v[e];
;                             }
;                             gst<u32x4>(p0 + (ai * HALF + m * 16) * pitch, pack8(v));
;                             asm volatile("" ::: "memory");
;                         }
.LBB0_419:
	s_andn2_b64 vcc, exec, s[60:61]
	s_cbranch_vccnz .LBB0_421
	v_and_b32_e32 v132, 64, v198
	v_xor_b32_e32 v0, 16, v198
	v_add_u32_e32 v132, 64, v132
	v_cmp_lt_i32_e32 vcc, v0, v132
	s_lshl_b32 s26, s71, 5
	s_mov_b32 s59, s27
	s_mov_b32 s19, s27
	s_mov_b32 s17, s27
	s_mov_b32 s15, s27
	v_cndmask_b32_e32 v0, v198, v0, vcc
	v_lshlrev_b32_e32 v0, 2, v0
	s_mov_b64 s[100:101], exec
	s_andn2_b64 vcc, s[54:55], s[56:57]
	ds_read_b32 v188, v154
	v_lshlrev_b32_e32 v159, 5, v2
	v_and_b32_e32 v159, 0xf9e0, v159
	global_load_dwordx4 v[164:167], v159, s[20:21] offset:16
	global_load_dwordx4 v[160:163], v159, s[20:21]
	global_load_dwordx4 v[172:175], v159, s[22:23] offset:16
	global_load_dwordx4 v[168:171], v159, s[22:23]
	s_waitcnt lgkmcnt(0)
	v_mul_f32_e32 v188, s9, v188
	v_pk_mul_f32 v[212:213], v[120:121], v[188:189] op_sel_hi:[1,0]
	v_pk_mul_f32 v[214:215], v[122:123], v[188:189] op_sel_hi:[1,0]
	v_pk_mul_f32 v[216:217], v[112:113], v[188:189] op_sel_hi:[1,0]
	v_pk_mul_f32 v[218:219], v[114:115], v[188:189] op_sel_hi:[1,0]
	ds_bpermute_b32 v228, v0, v212
	ds_bpermute_b32 v229, v0, v213
	ds_bpermute_b32 v230, v0, v214
	ds_bpermute_b32 v231, v0, v215
	ds_bpermute_b32 v132, v0, v216
	ds_bpermute_b32 v133, v0, v217
	ds_bpermute_b32 v134, v0, v218
	ds_bpermute_b32 v135, v0, v219
	ds_read_b32 v189, v154 offset:64
	v_or_b32_e32 v143, 0x200, v159
	global_load_dwordx4 v[180:183], v143, s[20:21] offset:16
	global_load_dwordx4 v[176:179], v143, s[20:21]
	global_load_dwordx4 v[190:193], v143, s[22:23] offset:16
	global_load_dwordx4 v[184:187], v143, s[22:23]
	s_waitcnt lgkmcnt(1)
	s_waitcnt vmcnt(4)
	v_pk_mul_f32 v[160:161], v[212:213], v[160:161]
	v_pk_mul_f32 v[162:163], v[214:215], v[162:163]
	v_pk_mul_f32 v[164:165], v[216:217], v[164:165]
	v_pk_mul_f32 v[166:167], v[218:219], v[166:167]
	v_pk_mul_f32 v[168:169], v[228:229], v[168:169]
	v_pk_mul_f32 v[170:171], v[230:231], v[170:171]
	v_pk_mul_f32 v[172:173], v[132:133], v[172:173]
	v_pk_mul_f32 v[174:175], v[134:135], v[174:175]
	s_mov_b64 exec, vcc
	v_pk_add_f32 v[212:213], v[160:161], v[168:169]
	v_pk_add_f32 v[214:215], v[162:163], v[170:171]
	v_pk_add_f32 v[216:217], v[164:165], v[172:173]
	v_pk_add_f32 v[218:219], v[166:167], v[174:175]
	s_mov_b64 exec, s[56:57]
	v_pk_add_f32 v[212:213], v[160:161], v[168:169] neg_lo:[0,1] neg_hi:[0,1]
	v_pk_add_f32 v[214:215], v[162:163], v[170:171] neg_lo:[0,1] neg_hi:[0,1]
	v_pk_add_f32 v[216:217], v[164:165], v[172:173] neg_lo:[0,1] neg_hi:[0,1]
	v_pk_add_f32 v[218:219], v[166:167], v[174:175] neg_lo:[0,1] neg_hi:[0,1]
	s_mov_b64 exec, s[100:101]
	v_cvt_pk_bf16_f32 v228, v212, v213
	v_cvt_pk_bf16_f32 v229, v214, v215
	v_cvt_pk_bf16_f32 v230, v216, v217
	v_cvt_pk_bf16_f32 v231, v218, v219
	global_store_dwordx4 v[140:141], v[228:231], off
	s_waitcnt lgkmcnt(0)
	v_mul_f32_e32 v189, s9, v189
	v_pk_mul_f32 v[212:213], v[100:101], v[188:189] op_sel:[0,1]
	v_pk_mul_f32 v[214:215], v[102:103], v[188:189] op_sel:[0,1]
	v_pk_mul_f32 v[216:217], v[88:89], v[188:189] op_sel:[0,1]
	v_pk_mul_f32 v[218:219], v[90:91], v[188:189] op_sel:[0,1]
	ds_bpermute_b32 v228, v0, v212
	ds_bpermute_b32 v229, v0, v213
	ds_bpermute_b32 v230, v0, v214
	ds_bpermute_b32 v231, v0, v215
	ds_bpermute_b32 v132, v0, v216
	ds_bpermute_b32 v133, v0, v217
	ds_bpermute_b32 v134, v0, v218
	ds_bpermute_b32 v135, v0, v219
	ds_read_b32 v188, v154 offset:128
	v_or_b32_e32 v143, 0x400, v159
	global_load_dwordx4 v[164:167], v143, s[20:21] offset:16
	global_load_dwordx4 v[160:163], v143, s[20:21]
	global_load_dwordx4 v[172:175], v143, s[22:23] offset:16
	global_load_dwordx4 v[168:171], v143, s[22:23]
	s_waitcnt lgkmcnt(1)
	s_waitcnt vmcnt(5)
	v_pk_mul_f32 v[176:177], v[212:213], v[176:177]
	v_pk_mul_f32 v[178:179], v[214:215], v[178:179]
	v_pk_mul_f32 v[180:181], v[216:217], v[180:181]
	v_pk_mul_f32 v[182:183], v[218:219], v[182:183]
	v_pk_mul_f32 v[184:185], v[228:229], v[184:185]
	v_pk_mul_f32 v[186:187], v[230:231], v[186:187]
	v_pk_mul_f32 v[190:191], v[132:133], v[190:191]
	v_pk_mul_f32 v[192:193], v[134:135], v[192:193]
	s_mov_b64 exec, vcc
	v_pk_add_f32 v[212:213], v[176:177], v[184:185]
	v_pk_add_f32 v[214:215], v[178:179], v[186:187]
	v_pk_add_f32 v[216:217], v[180:181], v[190:191]
	v_pk_add_f32 v[218:219], v[182:183], v[192:193]
	s_mov_b64 exec, s[56:57]
	v_pk_add_f32 v[212:213], v[176:177], v[184:185] neg_lo:[0,1] neg_hi:[0,1]
	v_pk_add_f32 v[214:215], v[178:179], v[186:187] neg_lo:[0,1] neg_hi:[0,1]
	v_pk_add_f32 v[216:217], v[180:181], v[190:191] neg_lo:[0,1] neg_hi:[0,1]
	v_pk_add_f32 v[218:219], v[182:183], v[192:193] neg_lo:[0,1] neg_hi:[0,1]
	s_mov_b64 exec, s[100:101]
	v_cvt_pk_bf16_f32 v228, v212, v213
	v_cvt_pk_bf16_f32 v229, v214, v215
	v_cvt_pk_bf16_f32 v230, v216, v217
	v_cvt_pk_bf16_f32 v231, v218, v219
	v_lshl_add_u64 v[132:133], v[140:141], 0, s[26:27]
	global_store_dwordx4 v[132:133], v[228:231], off
	s_waitcnt lgkmcnt(0)
	v_mul_f32_e32 v188, s9, v188
	v_pk_mul_f32 v[212:213], v[68:69], v[188:189] op_sel_hi:[1,0]
	v_pk_mul_f32 v[214:215], v[70:71], v[188:189] op_sel_hi:[1,0]
	v_pk_mul_f32 v[216:217], v[56:57], v[188:189] op_sel_hi:[1,0]
	v_pk_mul_f32 v[218:219], v[58:59], v[188:189] op_sel_hi:[1,0]
	ds_bpermute_b32 v228, v0, v212
	ds_bpermute_b32 v229, v0, v213
	ds_bpermute_b32 v230, v0, v214
	ds_bpermute_b32 v231, v0, v215
	ds_bpermute_b32 v132, v0, v216
	ds_bpermute_b32 v133, v0, v217
	ds_bpermute_b32 v134, v0, v218
	ds_bpermute_b32 v135, v0, v219
	ds_read_b32 v189, v154 offset:192
	v_or_b32_e32 v143, 0x600, v159
	global_load_dwordx4 v[180:183], v143, s[20:21] offset:16
	global_load_dwordx4 v[176:179], v143, s[20:21]
	global_load_dwordx4 v[190:193], v143, s[22:23] offset:16
	global_load_dwordx4 v[184:187], v143, s[22:23]
	s_waitcnt lgkmcnt(1)
; __device__ __forceinline__ u32x4 pack8(const float (&v)[8]) { u32x4 w; w.x = pk2(v[0], v[1]); w.y = pk2(v[2], v[3]); w.z = pk2(v[4], v[5]); w.w = pk2(v[6], v[7]); return w; }
;     __device__ __forceinline__ bool operator()(Acc& acc, const Unit& u, int wr, int wc, int fr, int fq, const LAS float* rstab) const {
;     ...
;                 if (rope) {
;                     const float sgn = (fq == 0) ? -1.f : 1.f;
; #pragma unroll
;                     for (int ai = 0; ai < 2; ++ai)
; #pragma unroll
;                         for (int m = 0; m < 4; ++m) {
;                             const float rs = rsp[ai * HALF + m * 16] * scale;
;                             const int pos = (rowb + ai * HALF + m * 16) & (SEQ - 1);
;                             const f32x4 c0 = gld<f32x4>(ropec + pos * 8), c1 = gld<f32x4>(ropec + pos * 8 + 4);
;                             const f32x4 s0 = gld<f32x4>(ropes + pos * 8), s1 = gld<f32x4>(ropes + pos * 8 + 4);
;                             float v[8];
; #pragma unroll
;                             for (int e = 0; e < 4; ++e) { v[e] = acc[ai][bj][m][0][e] * rs; v[4 + e] = acc[ai][bj][m][1][e] * rs; }
; #pragma unroll
;                             for (int e = 0; e < 8; ++e) {
;                                 const float p = __shfl_xor(v[e], 16);
;                                 const float cs = e < 4 ? c0[e & 3] : c1[e & 3], sn = e < 4 ? s0[e & 3] : s1[e & 3];
;                                 const float r = v[e] * cs + sgn * p * sn;
;                                 v[e] = (fq < 2) ? r : v[e];
;                             }
;                             gst<u32x4>(p0 + (ai * HALF + m * 16) * pitch, pack8(v));
;                             asm volatile("" ::: "memory");
;                         }
	s_waitcnt vmcnt(5)
	v_pk_mul_f32 v[160:161], v[212:213], v[160:161]
	v_pk_mul_f32 v[162:163], v[214:215], v[162:163]
	v_pk_mul_f32 v[164:165], v[216:217], v[164:165]
	v_pk_mul_f32 v[166:167], v[218:219], v[166:167]
	v_pk_mul_f32 v[168:169], v[228:229], v[168:169]
	v_pk_mul_f32 v[170:171], v[230:231], v[170:171]
	v_pk_mul_f32 v[172:173], v[132:133], v[172:173]
	v_pk_mul_f32 v[174:175], v[134:135], v[174:175]
	s_mov_b64 exec, vcc
	v_pk_add_f32 v[212:213], v[160:161], v[168:169]
	v_pk_add_f32 v[214:215], v[162:163], v[170:171]
	v_pk_add_f32 v[216:217], v[164:165], v[172:173]
	v_pk_add_f32 v[218:219], v[166:167], v[174:175]
	s_mov_b64 exec, s[56:57]
	v_pk_add_f32 v[212:213], v[160:161], v[168:169] neg_lo:[0,1] neg_hi:[0,1]
	v_pk_add_f32 v[214:215], v[162:163], v[170:171] neg_lo:[0,1] neg_hi:[0,1]
	v_pk_add_f32 v[216:217], v[164:165], v[172:173] neg_lo:[0,1] neg_hi:[0,1]
	v_pk_add_f32 v[218:219], v[166:167], v[174:175] neg_lo:[0,1] neg_hi:[0,1]
	s_mov_b64 exec, s[100:101]
	v_cvt_pk_bf16_f32 v228, v212, v213
	v_cvt_pk_bf16_f32 v229, v214, v215
	v_cvt_pk_bf16_f32 v230, v216, v217
	v_cvt_pk_bf16_f32 v231, v218, v219
	v_lshl_add_u64 v[132:133], s[26:27], 1, v[140:141]
	global_store_dwordx4 v[132:133], v[228:231], off
	s_lshl_b32 s26, s71, 8
	s_waitcnt lgkmcnt(0)
	v_mul_f32_e32 v189, s9, v189
	v_pk_mul_f32 v[212:213], v[36:37], v[188:189] op_sel:[0,1]
	v_pk_mul_f32 v[214:215], v[38:39], v[188:189] op_sel:[0,1]
	v_pk_mul_f32 v[216:217], v[28:29], v[188:189] op_sel:[0,1]
	v_pk_mul_f32 v[218:219], v[30:31], v[188:189] op_sel:[0,1]
	ds_bpermute_b32 v228, v0, v212
	ds_bpermute_b32 v229, v0, v213
	ds_bpermute_b32 v230, v0, v214
	ds_bpermute_b32 v231, v0, v215
	ds_bpermute_b32 v132, v0, v216
	ds_bpermute_b32 v133, v0, v217
	ds_bpermute_b32 v134, v0, v218
	ds_bpermute_b32 v135, v0, v219
	ds_read_b32 v188, v154 offset:512
	v_mov_b32_e32 v159, 0x400
	v_lshl_add_u32 v159, v2, 3, v159
	v_and_b32_e32 v159, 0x3e78, v159
	v_lshlrev_b32_e32 v159, 2, v159
	global_load_dwordx4 v[164:167], v159, s[20:21] offset:16
	global_load_dwordx4 v[160:163], v159, s[20:21]
	global_load_dwordx4 v[172:175], v159, s[22:23] offset:16
	global_load_dwordx4 v[168:171], v159, s[22:23]
	s_waitcnt lgkmcnt(1)
	s_waitcnt vmcnt(5)
	v_pk_mul_f32 v[176:177], v[212:213], v[176:177]
	v_pk_mul_f32 v[178:179], v[214:215], v[178:179]
	v_pk_mul_f32 v[180:181], v[216:217], v[180:181]
	v_pk_mul_f32 v[182:183], v[218:219], v[182:183]
	v_pk_mul_f32 v[184:185], v[228:229], v[184:185]
	v_pk_mul_f32 v[186:187], v[230:231], v[186:187]
	v_pk_mul_f32 v[190:191], v[132:133], v[190:191]
	v_pk_mul_f32 v[192:193], v[134:135], v[192:193]
	s_mov_b64 exec, vcc
	v_pk_add_f32 v[212:213], v[176:177], v[184:185]
	v_pk_add_f32 v[214:215], v[178:179], v[186:187]
	v_pk_add_f32 v[216:217], v[180:181], v[190:191]
	v_pk_add_f32 v[218:219], v[182:183], v[192:193]
	s_mov_b64 exec, s[56:57]
	v_pk_add_f32 v[212:213], v[176:177], v[184:185] neg_lo:[0,1] neg_hi:[0,1]
	v_pk_add_f32 v[214:215], v[178:179], v[186:187] neg_lo:[0,1] neg_hi:[0,1]
	v_pk_add_f32 v[216:217], v[180:181], v[190:191] neg_lo:[0,1] neg_hi:[0,1]
	v_pk_add_f32 v[218:219], v[182:183], v[192:193] neg_lo:[0,1] neg_hi:[0,1]
	s_mov_b64 exec, s[100:101]
	v_cvt_pk_bf16_f32 v228, v212, v213
	v_cvt_pk_bf16_f32 v229, v214, v215
	v_cvt_pk_bf16_f32 v230, v216, v217
	v_cvt_pk_bf16_f32 v231, v218, v219
	v_lshl_add_u64 v[132:133], s[58:59], 1, v[140:141]
	global_store_dwordx4 v[132:133], v[228:231], off
	s_waitcnt lgkmcnt(0)
	v_mul_f32_e32 v188, s9, v188
	v_pk_mul_f32 v[212:213], v[72:73], v[188:189] op_sel_hi:[1,0]
	v_pk_mul_f32 v[214:215], v[74:75], v[188:189] op_sel_hi:[1,0]
	v_pk_mul_f32 v[216:217], v[60:61], v[188:189] op_sel_hi:[1,0]
	v_pk_mul_f32 v[218:219], v[62:63], v[188:189] op_sel_hi:[1,0]
	ds_bpermute_b32 v228, v0, v212
	ds_bpermute_b32 v229, v0, v213
	ds_bpermute_b32 v230, v0, v214
	ds_bpermute_b32 v231, v0, v215
	ds_bpermute_b32 v132, v0, v216
	ds_bpermute_b32 v133, v0, v217
	ds_bpermute_b32 v134, v0, v218
	ds_bpermute_b32 v135, v0, v219
	ds_read_b32 v189, v154 offset:576
	v_or_b32_e32 v143, 0x200, v159
	global_load_dwordx4 v[180:183], v143, s[20:21] offset:16
	global_load_dwordx4 v[176:179], v143, s[20:21]
	global_load_dwordx4 v[190:193], v143, s[22:23] offset:16
	global_load_dwordx4 v[184:187], v143, s[22:23]
	s_waitcnt lgkmcnt(1)
	s_waitcnt vmcnt(5)
	v_pk_mul_f32 v[160:161], v[212:213], v[160:161]
	v_pk_mul_f32 v[162:163], v[214:215], v[162:163]
	v_pk_mul_f32 v[164:165], v[216:217], v[164:165]
	v_pk_mul_f32 v[166:167], v[218:219], v[166:167]
	v_pk_mul_f32 v[168:169], v[228:229], v[168:169]
	v_pk_mul_f32 v[170:171], v[230:231], v[170:171]
	v_pk_mul_f32 v[172:173], v[132:133], v[172:173]
	v_pk_mul_f32 v[174:175], v[134:135], v[174:175]
	s_mov_b64 exec, vcc
	v_pk_add_f32 v[212:213], v[160:161], v[168:169]
	v_pk_add_f32 v[214:215], v[162:163], v[170:171]
	v_pk_add_f32 v[216:217], v[164:165], v[172:173]
	v_pk_add_f32 v[218:219], v[166:167], v[174:175]
	s_mov_b64 exec, s[56:57]
	v_pk_add_f32 v[212:213], v[160:161], v[168:169] neg_lo:[0,1] neg_hi:[0,1]
	v_pk_add_f32 v[214:215], v[162:163], v[170:171] neg_lo:[0,1] neg_hi:[0,1]
	v_pk_add_f32 v[216:217], v[164:165], v[172:173] neg_lo:[0,1] neg_hi:[0,1]
	v_pk_add_f32 v[218:219], v[166:167], v[174:175] neg_lo:[0,1] neg_hi:[0,1]
	s_mov_b64 exec, s[100:101]
	v_cvt_pk_bf16_f32 v228, v212, v213
	v_cvt_pk_bf16_f32 v229, v214, v215
	v_cvt_pk_bf16_f32 v230, v216, v217
	v_cvt_pk_bf16_f32 v231, v218, v219
	v_lshl_add_u64 v[132:133], v[140:141], 0, s[26:27]
	global_store_dwordx4 v[132:133], v[228:231], off
	s_waitcnt lgkmcnt(0)
; __device__ __forceinline__ u32x4 pack8(const float (&v)[8]) { u32x4 w; w.x = pk2(v[0], v[1]); w.y = pk2(v[2], v[3]); w.z = pk2(v[4], v[5]); w.w = pk2(v[6], v[7]); return w; }
;     __device__ __forceinline__ bool operator()(Acc& acc, const Unit& u, int wr, int wc, int fr, int fq, const LAS float* rstab) const {
;     ...
;                 if (rope) {
;                     const float sgn = (fq == 0) ? -1.f : 1.f;
; #pragma unroll
;                     for (int ai = 0; ai < 2; ++ai)
; #pragma unroll
;                         for (int m = 0; m < 4; ++m) {
;                             const float rs = rsp[ai * HALF + m * 16] * scale;
;                             const int pos = (rowb + ai * HALF + m * 16) & (SEQ - 1);
;                             const f32x4 c0 = gld<f32x4>(ropec + pos * 8), c1 = gld<f32x4>(ropec + pos * 8 + 4);
;                             const f32x4 s0 = gld<f32x4>(ropes + pos * 8), s1 = gld<f32x4>(ropes + pos * 8 + 4);
;                             float v[8];
; #pragma unroll
;                             for (int e = 0; e < 4; ++e) { v[e] = acc[ai][bj][m][0][e] * rs; v[4 + e] = acc[ai][bj][m][1][e] * rs; }
; #pragma unroll
;                             for (int e = 0; e < 8; ++e) {
;                                 const float p = __shfl_xor(v[e], 16);
;                                 const float cs = e < 4 ? c0[e & 3] : c1[e & 3], sn = e < 4 ? s0[e & 3] : s1[e & 3];
;                                 const float r = v[e] * cs + sgn * p * sn;
;                                 v[e] = (fq < 2) ? r : v[e];
;                             }
;                             gst<u32x4>(p0 + (ai * HALF + m * 16) * pitch, pack8(v));
;                             asm volatile("" ::: "memory");
;                         }
	v_mul_f32_e32 v189, s9, v189
	v_pk_mul_f32 v[212:213], v[40:41], v[188:189] op_sel:[0,1]
	v_pk_mul_f32 v[214:215], v[42:43], v[188:189] op_sel:[0,1]
	v_pk_mul_f32 v[216:217], v[32:33], v[188:189] op_sel:[0,1]
	v_pk_mul_f32 v[218:219], v[34:35], v[188:189] op_sel:[0,1]
	ds_bpermute_b32 v228, v0, v212
	ds_bpermute_b32 v229, v0, v213
	ds_bpermute_b32 v230, v0, v214
	ds_bpermute_b32 v231, v0, v215
	ds_bpermute_b32 v132, v0, v216
	ds_bpermute_b32 v133, v0, v217
	ds_bpermute_b32 v134, v0, v218
	ds_bpermute_b32 v135, v0, v219
	ds_read_b32 v188, v154 offset:640
	v_or_b32_e32 v143, 0x400, v159
	global_load_dwordx4 v[164:167], v143, s[20:21] offset:16
	global_load_dwordx4 v[160:163], v143, s[20:21]
	global_load_dwordx4 v[172:175], v143, s[22:23] offset:16
	global_load_dwordx4 v[168:171], v143, s[22:23]
	s_waitcnt lgkmcnt(1)
	s_waitcnt vmcnt(5)
	v_pk_mul_f32 v[176:177], v[212:213], v[176:177]
	v_pk_mul_f32 v[178:179], v[214:215], v[178:179]
	v_pk_mul_f32 v[180:181], v[216:217], v[180:181]
	v_pk_mul_f32 v[182:183], v[218:219], v[182:183]
	v_pk_mul_f32 v[184:185], v[228:229], v[184:185]
	v_pk_mul_f32 v[186:187], v[230:231], v[186:187]
	v_pk_mul_f32 v[190:191], v[132:133], v[190:191]
	v_pk_mul_f32 v[192:193], v[134:135], v[192:193]
	s_mov_b64 exec, vcc
	v_pk_add_f32 v[212:213], v[176:177], v[184:185]
	v_pk_add_f32 v[214:215], v[178:179], v[186:187]
	v_pk_add_f32 v[216:217], v[180:181], v[190:191]
	v_pk_add_f32 v[218:219], v[182:183], v[192:193]
	s_mov_b64 exec, s[56:57]
	v_pk_add_f32 v[212:213], v[176:177], v[184:185] neg_lo:[0,1] neg_hi:[0,1]
	v_pk_add_f32 v[214:215], v[178:179], v[186:187] neg_lo:[0,1] neg_hi:[0,1]
	v_pk_add_f32 v[216:217], v[180:181], v[190:191] neg_lo:[0,1] neg_hi:[0,1]
	v_pk_add_f32 v[218:219], v[182:183], v[192:193] neg_lo:[0,1] neg_hi:[0,1]
	s_mov_b64 exec, s[100:101]
	v_cvt_pk_bf16_f32 v228, v212, v213
	v_cvt_pk_bf16_f32 v229, v214, v215
	v_cvt_pk_bf16_f32 v230, v216, v217
	v_cvt_pk_bf16_f32 v231, v218, v219
	v_lshl_add_u64 v[132:133], s[18:19], 1, v[140:141]
	global_store_dwordx4 v[132:133], v[228:231], off
	s_waitcnt lgkmcnt(0)
	v_mul_f32_e32 v188, s9, v188
	v_pk_mul_f32 v[212:213], v[16:17], v[188:189] op_sel_hi:[1,0]
	v_pk_mul_f32 v[214:215], v[18:19], v[188:189] op_sel_hi:[1,0]
	v_pk_mul_f32 v[216:217], v[12:13], v[188:189] op_sel_hi:[1,0]
	v_pk_mul_f32 v[218:219], v[14:15], v[188:189] op_sel_hi:[1,0]
	ds_bpermute_b32 v228, v0, v212
	ds_bpermute_b32 v229, v0, v213
	ds_bpermute_b32 v230, v0, v214
	ds_bpermute_b32 v231, v0, v215
	ds_bpermute_b32 v132, v0, v216
	ds_bpermute_b32 v133, v0, v217
	ds_bpermute_b32 v134, v0, v218
	ds_bpermute_b32 v135, v0, v219
	ds_read_b32 v189, v154 offset:704
	v_or_b32_e32 v143, 0x600, v159
	global_load_dwordx4 v[180:183], v143, s[20:21] offset:16
	global_load_dwordx4 v[176:179], v143, s[20:21]
	global_load_dwordx4 v[190:193], v143, s[22:23] offset:16
	global_load_dwordx4 v[184:187], v143, s[22:23]
	s_waitcnt lgkmcnt(1)
	s_waitcnt vmcnt(5)
	v_pk_mul_f32 v[160:161], v[212:213], v[160:161]
	v_pk_mul_f32 v[162:163], v[214:215], v[162:163]
	v_pk_mul_f32 v[164:165], v[216:217], v[164:165]
	v_pk_mul_f32 v[166:167], v[218:219], v[166:167]
	v_pk_mul_f32 v[168:169], v[228:229], v[168:169]
	v_pk_mul_f32 v[170:171], v[230:231], v[170:171]
	v_pk_mul_f32 v[172:173], v[132:133], v[172:173]
	v_pk_mul_f32 v[174:175], v[134:135], v[174:175]
	s_mov_b64 exec, vcc
	v_pk_add_f32 v[212:213], v[160:161], v[168:169]
	v_pk_add_f32 v[214:215], v[162:163], v[170:171]
	v_pk_add_f32 v[216:217], v[164:165], v[172:173]
	v_pk_add_f32 v[218:219], v[166:167], v[174:175]
	s_mov_b64 exec, s[56:57]
	v_pk_add_f32 v[212:213], v[160:161], v[168:169] neg_lo:[0,1] neg_hi:[0,1]
	v_pk_add_f32 v[214:215], v[162:163], v[170:171] neg_lo:[0,1] neg_hi:[0,1]
	v_pk_add_f32 v[216:217], v[164:165], v[172:173] neg_lo:[0,1] neg_hi:[0,1]
	v_pk_add_f32 v[218:219], v[166:167], v[174:175] neg_lo:[0,1] neg_hi:[0,1]
	s_mov_b64 exec, s[100:101]
	v_cvt_pk_bf16_f32 v228, v212, v213
	v_cvt_pk_bf16_f32 v229, v214, v215
	v_cvt_pk_bf16_f32 v230, v216, v217
	v_cvt_pk_bf16_f32 v231, v218, v219
	v_lshl_add_u64 v[132:133], s[16:17], 1, v[140:141]
	global_store_dwordx4 v[132:133], v[228:231], off
	s_waitcnt lgkmcnt(0)
	v_mul_f32_e32 v189, s9, v189
	v_pk_mul_f32 v[212:213], v[8:9], v[188:189] op_sel:[0,1]
	v_pk_mul_f32 v[214:215], v[10:11], v[188:189] op_sel:[0,1]
	v_pk_mul_f32 v[216:217], v[4:5], v[188:189] op_sel:[0,1]
	v_pk_mul_f32 v[218:219], v[6:7], v[188:189] op_sel:[0,1]
	ds_bpermute_b32 v228, v0, v212
	ds_bpermute_b32 v229, v0, v213
	ds_bpermute_b32 v230, v0, v214
	ds_bpermute_b32 v231, v0, v215
	ds_bpermute_b32 v132, v0, v216
	ds_bpermute_b32 v133, v0, v217
	ds_bpermute_b32 v134, v0, v218
	ds_bpermute_b32 v135, v0, v219
	s_waitcnt lgkmcnt(0)
	s_waitcnt vmcnt(1)
	v_pk_mul_f32 v[176:177], v[212:213], v[176:177]
	v_pk_mul_f32 v[178:179], v[214:215], v[178:179]
	v_pk_mul_f32 v[180:181], v[216:217], v[180:181]
	v_pk_mul_f32 v[182:183], v[218:219], v[182:183]
	v_pk_mul_f32 v[184:185], v[228:229], v[184:185]
	v_pk_mul_f32 v[186:187], v[230:231], v[186:187]
	v_pk_mul_f32 v[190:191], v[132:133], v[190:191]
	v_pk_mul_f32 v[192:193], v[134:135], v[192:193]
	s_mov_b64 exec, vcc
	v_pk_add_f32 v[212:213], v[176:177], v[184:185]
	v_pk_add_f32 v[214:215], v[178:179], v[186:187]
	v_pk_add_f32 v[216:217], v[180:181], v[190:191]
	v_pk_add_f32 v[218:219], v[182:183], v[192:193]
	s_mov_b64 exec, s[56:57]
	v_pk_add_f32 v[212:213], v[176:177], v[184:185] neg_lo:[0,1] neg_hi:[0,1]
	v_pk_add_f32 v[214:215], v[178:179], v[186:187] neg_lo:[0,1] neg_hi:[0,1]
	v_pk_add_f32 v[216:217], v[180:181], v[190:191] neg_lo:[0,1] neg_hi:[0,1]
	v_pk_add_f32 v[218:219], v[182:183], v[192:193] neg_lo:[0,1] neg_hi:[0,1]
	s_mov_b64 exec, s[100:101]
	v_cvt_pk_bf16_f32 v228, v212, v213
	v_cvt_pk_bf16_f32 v229, v214, v215
	v_cvt_pk_bf16_f32 v230, v216, v217
	v_cvt_pk_bf16_f32 v231, v218, v219
	v_lshl_add_u64 v[132:133], s[14:15], 1, v[140:141]
	global_store_dwordx4 v[132:133], v[228:231], off

; __device__ __forceinline__ u32x4 pack8(const float (&v)[8]) { u32x4 w; w.x = pk2(v[0], v[1]); w.y = pk2(v[2], v[3]); w.z = pk2(v[4], v[5]); w.w = pk2(v[6], v[7]); return w; }
;     __device__ __forceinline__ bool operator()(Acc& acc, const Unit& u, int wr, int wc, int fr, int fq, const LAS float* rstab) const {
;     ...
;                 if (rope) {
;                     const float sgn = (fq == 0) ? -1.f : 1.f;
; #pragma unroll
;                     for (int ai = 0; ai < 2; ++ai)
; #pragma unroll
;                         for (int m = 0; m < 4; ++m) {
;                             const float rs = rsp[ai * HALF + m * 16] * scale;
;                             const int pos = (rowb + ai * HALF + m * 16) & (SEQ - 1);
;                             const f32x4 c0 = gld<f32x4>(ropec + pos * 8), c1 = gld<f32x4>(ropec + pos * 8 + 4);
;                             const f32x4 s0 = gld<f32x4>(ropes + pos * 8), s1 = gld<f32x4>(ropes + pos * 8 + 4);
;                             float v[8];
; #pragma unroll
;                             for (int e = 0; e < 4; ++e) { v[e] = acc[ai][bj][m][0][e] * rs; v[4 + e] = acc[ai][bj][m][1][e] * rs; }
; #pragma unroll
;                             for (int e = 0; e < 8; ++e) {
;                                 const float p = __shfl_xor(v[e], 16);
;                                 const float cs = e < 4 ? c0[e & 3] : c1[e & 3], sn = e < 4 ? s0[e & 3] : s1[e & 3];
;                                 const float r = v[e] * cs + sgn * p * sn;
;                                 v[e] = (fq < 2) ? r : v[e];
;                             }
;                             gst<u32x4>(p0 + (ai * HALF + m * 16) * pitch, pack8(v));
;                             asm volatile("" ::: "memory");
;                         }
.LBB0_450:
	s_andn2_b64 vcc, exec, s[58:59]
	s_cbranch_vccnz .LBB0_452
	v_and_b32_e32 v132, 64, v198
	v_xor_b32_e32 v0, 16, v198
	v_add_u32_e32 v132, 64, v132
	v_cmp_lt_i32_e32 vcc, v0, v132
	s_lshl_b32 s26, s61, 5
	s_mov_b32 s19, s27
	s_mov_b32 s17, s27
	s_mov_b32 s15, s27
	s_mov_b32 s13, s27
	v_cndmask_b32_e32 v0, v198, v0, vcc
	v_lshlrev_b32_e32 v0, 2, v0
	s_mov_b64 s[100:101], exec
	s_andn2_b64 vcc, s[54:55], s[56:57]
	ds_read_b32 v188, v154
	v_lshlrev_b32_e32 v159, 5, v2
	v_and_b32_e32 v159, 0xf9e0, v159
	global_load_dwordx4 v[164:167], v159, s[20:21] offset:16
	global_load_dwordx4 v[160:163], v159, s[20:21]
	global_load_dwordx4 v[172:175], v159, s[22:23] offset:16
	global_load_dwordx4 v[168:171], v159, s[22:23]
	s_waitcnt lgkmcnt(0)
	v_mul_f32_e32 v188, s9, v188
	v_pk_mul_f32 v[212:213], v[128:129], v[188:189] op_sel_hi:[1,0]
	v_pk_mul_f32 v[214:215], v[130:131], v[188:189] op_sel_hi:[1,0]
	v_pk_mul_f32 v[216:217], v[124:125], v[188:189] op_sel_hi:[1,0]
	v_pk_mul_f32 v[218:219], v[126:127], v[188:189] op_sel_hi:[1,0]
	ds_bpermute_b32 v228, v0, v212
	ds_bpermute_b32 v229, v0, v213
	ds_bpermute_b32 v230, v0, v214
	ds_bpermute_b32 v231, v0, v215
	ds_bpermute_b32 v132, v0, v216
	ds_bpermute_b32 v133, v0, v217
	ds_bpermute_b32 v134, v0, v218
	ds_bpermute_b32 v135, v0, v219
	ds_read_b32 v189, v154 offset:64
	v_or_b32_e32 v136, 0x200, v159
	global_load_dwordx4 v[180:183], v136, s[20:21] offset:16
	global_load_dwordx4 v[176:179], v136, s[20:21]
	global_load_dwordx4 v[190:193], v136, s[22:23] offset:16
	global_load_dwordx4 v[184:187], v136, s[22:23]
	s_waitcnt lgkmcnt(1)
	s_waitcnt vmcnt(4)
	v_pk_mul_f32 v[160:161], v[212:213], v[160:161]
	v_pk_mul_f32 v[162:163], v[214:215], v[162:163]
	v_pk_mul_f32 v[164:165], v[216:217], v[164:165]
	v_pk_mul_f32 v[166:167], v[218:219], v[166:167]
	v_pk_mul_f32 v[168:169], v[228:229], v[168:169]
	v_pk_mul_f32 v[170:171], v[230:231], v[170:171]
	v_pk_mul_f32 v[172:173], v[132:133], v[172:173]
	v_pk_mul_f32 v[174:175], v[134:135], v[174:175]
	s_mov_b64 exec, vcc
	v_pk_add_f32 v[212:213], v[160:161], v[168:169]
	v_pk_add_f32 v[214:215], v[162:163], v[170:171]
	v_pk_add_f32 v[216:217], v[164:165], v[172:173]
	v_pk_add_f32 v[218:219], v[166:167], v[174:175]
	s_mov_b64 exec, s[56:57]
	v_pk_add_f32 v[212:213], v[160:161], v[168:169] neg_lo:[0,1] neg_hi:[0,1]
	v_pk_add_f32 v[214:215], v[162:163], v[170:171] neg_lo:[0,1] neg_hi:[0,1]
	v_pk_add_f32 v[216:217], v[164:165], v[172:173] neg_lo:[0,1] neg_hi:[0,1]
	v_pk_add_f32 v[218:219], v[166:167], v[174:175] neg_lo:[0,1] neg_hi:[0,1]
	s_mov_b64 exec, s[100:101]
	v_cvt_pk_bf16_f32 v228, v212, v213
	v_cvt_pk_bf16_f32 v229, v214, v215
	v_cvt_pk_bf16_f32 v230, v216, v217
	v_cvt_pk_bf16_f32 v231, v218, v219
	global_store_dwordx4 v[142:143], v[228:231], off
	s_waitcnt lgkmcnt(0)
	v_mul_f32_e32 v189, s9, v189
	v_pk_mul_f32 v[212:213], v[116:117], v[188:189] op_sel:[0,1]
	v_pk_mul_f32 v[214:215], v[118:119], v[188:189] op_sel:[0,1]
	v_pk_mul_f32 v[216:217], v[108:109], v[188:189] op_sel:[0,1]
	v_pk_mul_f32 v[218:219], v[110:111], v[188:189] op_sel:[0,1]
	ds_bpermute_b32 v228, v0, v212
	ds_bpermute_b32 v229, v0, v213
	ds_bpermute_b32 v230, v0, v214
	ds_bpermute_b32 v231, v0, v215
	ds_bpermute_b32 v132, v0, v216
	ds_bpermute_b32 v133, v0, v217
	ds_bpermute_b32 v134, v0, v218
	ds_bpermute_b32 v135, v0, v219
	ds_read_b32 v188, v154 offset:128
	v_or_b32_e32 v136, 0x400, v159
	global_load_dwordx4 v[164:167], v136, s[20:21] offset:16
	global_load_dwordx4 v[160:163], v136, s[20:21]
	global_load_dwordx4 v[172:175], v136, s[22:23] offset:16
	global_load_dwordx4 v[168:171], v136, s[22:23]
	s_waitcnt lgkmcnt(1)
	s_waitcnt vmcnt(5)
	v_pk_mul_f32 v[176:177], v[212:213], v[176:177]
	v_pk_mul_f32 v[178:179], v[214:215], v[178:179]
	v_pk_mul_f32 v[180:181], v[216:217], v[180:181]
	v_pk_mul_f32 v[182:183], v[218:219], v[182:183]
	v_pk_mul_f32 v[184:185], v[228:229], v[184:185]
	v_pk_mul_f32 v[186:187], v[230:231], v[186:187]
	v_pk_mul_f32 v[190:191], v[132:133], v[190:191]
	v_pk_mul_f32 v[192:193], v[134:135], v[192:193]
	s_mov_b64 exec, vcc
	v_pk_add_f32 v[212:213], v[176:177], v[184:185]
	v_pk_add_f32 v[214:215], v[178:179], v[186:187]
	v_pk_add_f32 v[216:217], v[180:181], v[190:191]
	v_pk_add_f32 v[218:219], v[182:183], v[192:193]
	s_mov_b64 exec, s[56:57]
	v_pk_add_f32 v[212:213], v[176:177], v[184:185] neg_lo:[0,1] neg_hi:[0,1]
	v_pk_add_f32 v[214:215], v[178:179], v[186:187] neg_lo:[0,1] neg_hi:[0,1]
	v_pk_add_f32 v[216:217], v[180:181], v[190:191] neg_lo:[0,1] neg_hi:[0,1]
	v_pk_add_f32 v[218:219], v[182:183], v[192:193] neg_lo:[0,1] neg_hi:[0,1]
	s_mov_b64 exec, s[100:101]
	v_cvt_pk_bf16_f32 v228, v212, v213
	v_cvt_pk_bf16_f32 v229, v214, v215
	v_cvt_pk_bf16_f32 v230, v216, v217
	v_cvt_pk_bf16_f32 v231, v218, v219
	v_lshl_add_u64 v[132:133], v[142:143], 0, s[26:27]
	global_store_dwordx4 v[132:133], v[228:231], off
	s_waitcnt lgkmcnt(0)
	v_mul_f32_e32 v188, s9, v188
	v_pk_mul_f32 v[212:213], v[92:93], v[188:189] op_sel_hi:[1,0]
	v_pk_mul_f32 v[214:215], v[94:95], v[188:189] op_sel_hi:[1,0]
	v_pk_mul_f32 v[216:217], v[80:81], v[188:189] op_sel_hi:[1,0]
	v_pk_mul_f32 v[218:219], v[82:83], v[188:189] op_sel_hi:[1,0]
	ds_bpermute_b32 v228, v0, v212
	ds_bpermute_b32 v229, v0, v213
	ds_bpermute_b32 v230, v0, v214
	ds_bpermute_b32 v231, v0, v215
	ds_bpermute_b32 v132, v0, v216
	ds_bpermute_b32 v133, v0, v217
	ds_bpermute_b32 v134, v0, v218
	ds_bpermute_b32 v135, v0, v219
	ds_read_b32 v189, v154 offset:192
	v_or_b32_e32 v136, 0x600, v159
	global_load_dwordx4 v[180:183], v136, s[20:21] offset:16
	global_load_dwordx4 v[176:179], v136, s[20:21]
	global_load_dwordx4 v[190:193], v136, s[22:23] offset:16
	global_load_dwordx4 v[184:187], v136, s[22:23]
	s_waitcnt lgkmcnt(1)
; __device__ __forceinline__ u32x4 pack8(const float (&v)[8]) { u32x4 w; w.x = pk2(v[0], v[1]); w.y = pk2(v[2], v[3]); w.z = pk2(v[4], v[5]); w.w = pk2(v[6], v[7]); return w; }
;     __device__ __forceinline__ bool operator()(Acc& acc, const Unit& u, int wr, int wc, int fr, int fq, const LAS float* rstab) const {
;     ...
;                 if (rope) {
;                     const float sgn = (fq == 0) ? -1.f : 1.f;
; #pragma unroll
;                     for (int ai = 0; ai < 2; ++ai)
; #pragma unroll
;                         for (int m = 0; m < 4; ++m) {
;                             const float rs = rsp[ai * HALF + m * 16] * scale;
;                             const int pos = (rowb + ai * HALF + m * 16) & (SEQ - 1);
;                             const f32x4 c0 = gld<f32x4>(ropec + pos * 8), c1 = gld<f32x4>(ropec + pos * 8 + 4);
;                             const f32x4 s0 = gld<f32x4>(ropes + pos * 8), s1 = gld<f32x4>(ropes + pos * 8 + 4);
;                             float v[8];
; #pragma unroll
;                             for (int e = 0; e < 4; ++e) { v[e] = acc[ai][bj][m][0][e] * rs; v[4 + e] = acc[ai][bj][m][1][e] * rs; }
; #pragma unroll
;                             for (int e = 0; e < 8; ++e) {
;                                 const float p = __shfl_xor(v[e], 16);
;                                 const float cs = e < 4 ? c0[e & 3] : c1[e & 3], sn = e < 4 ? s0[e & 3] : s1[e & 3];
;                                 const float r = v[e] * cs + sgn * p * sn;
;                                 v[e] = (fq < 2) ? r : v[e];
;                             }
;                             gst<u32x4>(p0 + (ai * HALF + m * 16) * pitch, pack8(v));
;                             asm volatile("" ::: "memory");
;                         }
	s_waitcnt vmcnt(5)
	v_pk_mul_f32 v[160:161], v[212:213], v[160:161]
	v_pk_mul_f32 v[162:163], v[214:215], v[162:163]
	v_pk_mul_f32 v[164:165], v[216:217], v[164:165]
	v_pk_mul_f32 v[166:167], v[218:219], v[166:167]
	v_pk_mul_f32 v[168:169], v[228:229], v[168:169]
	v_pk_mul_f32 v[170:171], v[230:231], v[170:171]
	v_pk_mul_f32 v[172:173], v[132:133], v[172:173]
	v_pk_mul_f32 v[174:175], v[134:135], v[174:175]
	s_mov_b64 exec, vcc
	v_pk_add_f32 v[212:213], v[160:161], v[168:169]
	v_pk_add_f32 v[214:215], v[162:163], v[170:171]
	v_pk_add_f32 v[216:217], v[164:165], v[172:173]
	v_pk_add_f32 v[218:219], v[166:167], v[174:175]
	s_mov_b64 exec, s[56:57]
	v_pk_add_f32 v[212:213], v[160:161], v[168:169] neg_lo:[0,1] neg_hi:[0,1]
	v_pk_add_f32 v[214:215], v[162:163], v[170:171] neg_lo:[0,1] neg_hi:[0,1]
	v_pk_add_f32 v[216:217], v[164:165], v[172:173] neg_lo:[0,1] neg_hi:[0,1]
	v_pk_add_f32 v[218:219], v[166:167], v[174:175] neg_lo:[0,1] neg_hi:[0,1]
	s_mov_b64 exec, s[100:101]
	v_cvt_pk_bf16_f32 v228, v212, v213
	v_cvt_pk_bf16_f32 v229, v214, v215
	v_cvt_pk_bf16_f32 v230, v216, v217
	v_cvt_pk_bf16_f32 v231, v218, v219
	v_lshl_add_u64 v[132:133], s[26:27], 1, v[142:143]
	global_store_dwordx4 v[132:133], v[228:231], off
	s_lshl_b32 s26, s61, 8
	s_waitcnt lgkmcnt(0)
	v_mul_f32_e32 v189, s9, v189
	v_pk_mul_f32 v[212:213], v[64:65], v[188:189] op_sel:[0,1]
	v_pk_mul_f32 v[214:215], v[66:67], v[188:189] op_sel:[0,1]
	v_pk_mul_f32 v[216:217], v[48:49], v[188:189] op_sel:[0,1]
	v_pk_mul_f32 v[218:219], v[50:51], v[188:189] op_sel:[0,1]
	ds_bpermute_b32 v228, v0, v212
	ds_bpermute_b32 v229, v0, v213
	ds_bpermute_b32 v230, v0, v214
	ds_bpermute_b32 v231, v0, v215
	ds_bpermute_b32 v132, v0, v216
	ds_bpermute_b32 v133, v0, v217
	ds_bpermute_b32 v134, v0, v218
	ds_bpermute_b32 v135, v0, v219
	ds_read_b32 v188, v154 offset:512
	v_mov_b32_e32 v159, 0x400
	v_lshl_add_u32 v159, v2, 3, v159
	v_and_b32_e32 v159, 0x3e78, v159
	v_lshlrev_b32_e32 v159, 2, v159
	global_load_dwordx4 v[164:167], v159, s[20:21] offset:16
	global_load_dwordx4 v[160:163], v159, s[20:21]
	global_load_dwordx4 v[172:175], v159, s[22:23] offset:16
	global_load_dwordx4 v[168:171], v159, s[22:23]
	s_waitcnt lgkmcnt(1)
	s_waitcnt vmcnt(5)
	v_pk_mul_f32 v[176:177], v[212:213], v[176:177]
	v_pk_mul_f32 v[178:179], v[214:215], v[178:179]
	v_pk_mul_f32 v[180:181], v[216:217], v[180:181]
	v_pk_mul_f32 v[182:183], v[218:219], v[182:183]
	v_pk_mul_f32 v[184:185], v[228:229], v[184:185]
	v_pk_mul_f32 v[186:187], v[230:231], v[186:187]
	v_pk_mul_f32 v[190:191], v[132:133], v[190:191]
	v_pk_mul_f32 v[192:193], v[134:135], v[192:193]
	s_mov_b64 exec, vcc
	v_pk_add_f32 v[212:213], v[176:177], v[184:185]
	v_pk_add_f32 v[214:215], v[178:179], v[186:187]
	v_pk_add_f32 v[216:217], v[180:181], v[190:191]
	v_pk_add_f32 v[218:219], v[182:183], v[192:193]
	s_mov_b64 exec, s[56:57]
	v_pk_add_f32 v[212:213], v[176:177], v[184:185] neg_lo:[0,1] neg_hi:[0,1]
	v_pk_add_f32 v[214:215], v[178:179], v[186:187] neg_lo:[0,1] neg_hi:[0,1]
	v_pk_add_f32 v[216:217], v[180:181], v[190:191] neg_lo:[0,1] neg_hi:[0,1]
	v_pk_add_f32 v[218:219], v[182:183], v[192:193] neg_lo:[0,1] neg_hi:[0,1]
	s_mov_b64 exec, s[100:101]
	v_cvt_pk_bf16_f32 v228, v212, v213
	v_cvt_pk_bf16_f32 v229, v214, v215
	v_cvt_pk_bf16_f32 v230, v216, v217
	v_cvt_pk_bf16_f32 v231, v218, v219
	v_lshl_add_u64 v[132:133], s[18:19], 1, v[142:143]
	global_store_dwordx4 v[132:133], v[228:231], off
	s_waitcnt lgkmcnt(0)
	v_mul_f32_e32 v188, s9, v188
	v_pk_mul_f32 v[212:213], v[96:97], v[188:189] op_sel_hi:[1,0]
	v_pk_mul_f32 v[214:215], v[98:99], v[188:189] op_sel_hi:[1,0]
	v_pk_mul_f32 v[216:217], v[104:105], v[188:189] op_sel_hi:[1,0]
	v_pk_mul_f32 v[218:219], v[106:107], v[188:189] op_sel_hi:[1,0]
	ds_bpermute_b32 v228, v0, v212
	ds_bpermute_b32 v229, v0, v213
	ds_bpermute_b32 v230, v0, v214
	ds_bpermute_b32 v231, v0, v215
	ds_bpermute_b32 v132, v0, v216
	ds_bpermute_b32 v133, v0, v217
	ds_bpermute_b32 v134, v0, v218
	ds_bpermute_b32 v135, v0, v219
	ds_read_b32 v189, v154 offset:576
	v_or_b32_e32 v136, 0x200, v159
	global_load_dwordx4 v[180:183], v136, s[20:21] offset:16
	global_load_dwordx4 v[176:179], v136, s[20:21]
	global_load_dwordx4 v[190:193], v136, s[22:23] offset:16
	global_load_dwordx4 v[184:187], v136, s[22:23]
	s_waitcnt lgkmcnt(1)
	s_waitcnt vmcnt(5)
	v_pk_mul_f32 v[160:161], v[212:213], v[160:161]
	v_pk_mul_f32 v[162:163], v[214:215], v[162:163]
	v_pk_mul_f32 v[164:165], v[216:217], v[164:165]
	v_pk_mul_f32 v[166:167], v[218:219], v[166:167]
	v_pk_mul_f32 v[168:169], v[228:229], v[168:169]
	v_pk_mul_f32 v[170:171], v[230:231], v[170:171]
	v_pk_mul_f32 v[172:173], v[132:133], v[172:173]
	v_pk_mul_f32 v[174:175], v[134:135], v[174:175]
	s_mov_b64 exec, vcc
	v_pk_add_f32 v[212:213], v[160:161], v[168:169]
	v_pk_add_f32 v[214:215], v[162:163], v[170:171]
	v_pk_add_f32 v[216:217], v[164:165], v[172:173]
	v_pk_add_f32 v[218:219], v[166:167], v[174:175]
	s_mov_b64 exec, s[56:57]
	v_pk_add_f32 v[212:213], v[160:161], v[168:169] neg_lo:[0,1] neg_hi:[0,1]
	v_pk_add_f32 v[214:215], v[162:163], v[170:171] neg_lo:[0,1] neg_hi:[0,1]
	v_pk_add_f32 v[216:217], v[164:165], v[172:173] neg_lo:[0,1] neg_hi:[0,1]
	v_pk_add_f32 v[218:219], v[166:167], v[174:175] neg_lo:[0,1] neg_hi:[0,1]
	s_mov_b64 exec, s[100:101]
	v_cvt_pk_bf16_f32 v228, v212, v213
	v_cvt_pk_bf16_f32 v229, v214, v215
	v_cvt_pk_bf16_f32 v230, v216, v217
	v_cvt_pk_bf16_f32 v231, v218, v219
	v_lshl_add_u64 v[132:133], v[142:143], 0, s[26:27]
	global_store_dwordx4 v[132:133], v[228:231], off
	s_waitcnt lgkmcnt(0)
; __device__ __forceinline__ u32x4 pack8(const float (&v)[8]) { u32x4 w; w.x = pk2(v[0], v[1]); w.y = pk2(v[2], v[3]); w.z = pk2(v[4], v[5]); w.w = pk2(v[6], v[7]); return w; }
;     __device__ __forceinline__ bool operator()(Acc& acc, const Unit& u, int wr, int wc, int fr, int fq, const LAS float* rstab) const {
;     ...
;                 if (rope) {
;                     const float sgn = (fq == 0) ? -1.f : 1.f;
; #pragma unroll
;                     for (int ai = 0; ai < 2; ++ai)
; #pragma unroll
;                         for (int m = 0; m < 4; ++m) {
;                             const float rs = rsp[ai * HALF + m * 16] * scale;
;                             const int pos = (rowb + ai * HALF + m * 16) & (SEQ - 1);
;                             const f32x4 c0 = gld<f32x4>(ropec + pos * 8), c1 = gld<f32x4>(ropec + pos * 8 + 4);
;                             const f32x4 s0 = gld<f32x4>(ropes + pos * 8), s1 = gld<f32x4>(ropes + pos * 8 + 4);
;                             float v[8];
; #pragma unroll
;                             for (int e = 0; e < 4; ++e) { v[e] = acc[ai][bj][m][0][e] * rs; v[4 + e] = acc[ai][bj][m][1][e] * rs; }
; #pragma unroll
;                             for (int e = 0; e < 8; ++e) {
;                                 const float p = __shfl_xor(v[e], 16);
;                                 const float cs = e < 4 ? c0[e & 3] : c1[e & 3], sn = e < 4 ? s0[e & 3] : s1[e & 3];
;                                 const float r = v[e] * cs + sgn * p * sn;
;                                 v[e] = (fq < 2) ? r : v[e];
;                             }
;                             gst<u32x4>(p0 + (ai * HALF + m * 16) * pitch, pack8(v));
;                             asm volatile("" ::: "memory");
;                         }
	v_mul_f32_e32 v189, s9, v189
	v_pk_mul_f32 v[212:213], v[84:85], v[188:189] op_sel:[0,1]
	v_pk_mul_f32 v[214:215], v[86:87], v[188:189] op_sel:[0,1]
	v_pk_mul_f32 v[216:217], v[76:77], v[188:189] op_sel:[0,1]
	v_pk_mul_f32 v[218:219], v[78:79], v[188:189] op_sel:[0,1]
	ds_bpermute_b32 v228, v0, v212
	ds_bpermute_b32 v229, v0, v213
	ds_bpermute_b32 v230, v0, v214
	ds_bpermute_b32 v231, v0, v215
	ds_bpermute_b32 v132, v0, v216
	ds_bpermute_b32 v133, v0, v217
	ds_bpermute_b32 v134, v0, v218
	ds_bpermute_b32 v135, v0, v219
	ds_read_b32 v188, v154 offset:640
	v_or_b32_e32 v136, 0x400, v159
	global_load_dwordx4 v[164:167], v136, s[20:21] offset:16
	global_load_dwordx4 v[160:163], v136, s[20:21]
	global_load_dwordx4 v[172:175], v136, s[22:23] offset:16
	global_load_dwordx4 v[168:171], v136, s[22:23]
	s_waitcnt lgkmcnt(1)
	s_waitcnt vmcnt(5)
	v_pk_mul_f32 v[176:177], v[212:213], v[176:177]
	v_pk_mul_f32 v[178:179], v[214:215], v[178:179]
	v_pk_mul_f32 v[180:181], v[216:217], v[180:181]
	v_pk_mul_f32 v[182:183], v[218:219], v[182:183]
	v_pk_mul_f32 v[184:185], v[228:229], v[184:185]
	v_pk_mul_f32 v[186:187], v[230:231], v[186:187]
	v_pk_mul_f32 v[190:191], v[132:133], v[190:191]
	v_pk_mul_f32 v[192:193], v[134:135], v[192:193]
	s_mov_b64 exec, vcc
	v_pk_add_f32 v[212:213], v[176:177], v[184:185]
	v_pk_add_f32 v[214:215], v[178:179], v[186:187]
	v_pk_add_f32 v[216:217], v[180:181], v[190:191]
	v_pk_add_f32 v[218:219], v[182:183], v[192:193]
	s_mov_b64 exec, s[56:57]
	v_pk_add_f32 v[212:213], v[176:177], v[184:185] neg_lo:[0,1] neg_hi:[0,1]
	v_pk_add_f32 v[214:215], v[178:179], v[186:187] neg_lo:[0,1] neg_hi:[0,1]
	v_pk_add_f32 v[216:217], v[180:181], v[190:191] neg_lo:[0,1] neg_hi:[0,1]
	v_pk_add_f32 v[218:219], v[182:183], v[192:193] neg_lo:[0,1] neg_hi:[0,1]
	s_mov_b64 exec, s[100:101]
	v_cvt_pk_bf16_f32 v228, v212, v213
	v_cvt_pk_bf16_f32 v229, v214, v215
	v_cvt_pk_bf16_f32 v230, v216, v217
	v_cvt_pk_bf16_f32 v231, v218, v219
	v_lshl_add_u64 v[132:133], s[16:17], 1, v[142:143]
	global_store_dwordx4 v[132:133], v[228:231], off
	s_waitcnt lgkmcnt(0)
	v_mul_f32_e32 v188, s9, v188
	v_pk_mul_f32 v[212:213], v[52:53], v[188:189] op_sel_hi:[1,0]
	v_pk_mul_f32 v[214:215], v[54:55], v[188:189] op_sel_hi:[1,0]
	v_pk_mul_f32 v[216:217], v[44:45], v[188:189] op_sel_hi:[1,0]
	v_pk_mul_f32 v[218:219], v[46:47], v[188:189] op_sel_hi:[1,0]
	ds_bpermute_b32 v228, v0, v212
	ds_bpermute_b32 v229, v0, v213
	ds_bpermute_b32 v230, v0, v214
	ds_bpermute_b32 v231, v0, v215
	ds_bpermute_b32 v132, v0, v216
	ds_bpermute_b32 v133, v0, v217
	ds_bpermute_b32 v134, v0, v218
	ds_bpermute_b32 v135, v0, v219
	ds_read_b32 v189, v154 offset:704
	v_or_b32_e32 v136, 0x600, v159
	global_load_dwordx4 v[180:183], v136, s[20:21] offset:16
	global_load_dwordx4 v[176:179], v136, s[20:21]
	global_load_dwordx4 v[190:193], v136, s[22:23] offset:16
	global_load_dwordx4 v[184:187], v136, s[22:23]
	s_waitcnt lgkmcnt(1)
	s_waitcnt vmcnt(5)
	v_pk_mul_f32 v[160:161], v[212:213], v[160:161]
	v_pk_mul_f32 v[162:163], v[214:215], v[162:163]
	v_pk_mul_f32 v[164:165], v[216:217], v[164:165]
	v_pk_mul_f32 v[166:167], v[218:219], v[166:167]
	v_pk_mul_f32 v[168:169], v[228:229], v[168:169]
	v_pk_mul_f32 v[170:171], v[230:231], v[170:171]
	v_pk_mul_f32 v[172:173], v[132:133], v[172:173]
	v_pk_mul_f32 v[174:175], v[134:135], v[174:175]
	s_mov_b64 exec, vcc
	v_pk_add_f32 v[212:213], v[160:161], v[168:169]
	v_pk_add_f32 v[214:215], v[162:163], v[170:171]
	v_pk_add_f32 v[216:217], v[164:165], v[172:173]
	v_pk_add_f32 v[218:219], v[166:167], v[174:175]
	s_mov_b64 exec, s[56:57]
	v_pk_add_f32 v[212:213], v[160:161], v[168:169] neg_lo:[0,1] neg_hi:[0,1]
	v_pk_add_f32 v[214:215], v[162:163], v[170:171] neg_lo:[0,1] neg_hi:[0,1]
	v_pk_add_f32 v[216:217], v[164:165], v[172:173] neg_lo:[0,1] neg_hi:[0,1]
	v_pk_add_f32 v[218:219], v[166:167], v[174:175] neg_lo:[0,1] neg_hi:[0,1]
	s_mov_b64 exec, s[100:101]
	v_cvt_pk_bf16_f32 v228, v212, v213
	v_cvt_pk_bf16_f32 v229, v214, v215
	v_cvt_pk_bf16_f32 v230, v216, v217
	v_cvt_pk_bf16_f32 v231, v218, v219
	v_lshl_add_u64 v[132:133], s[14:15], 1, v[142:143]
	global_store_dwordx4 v[132:133], v[228:231], off
	s_waitcnt lgkmcnt(0)
	v_mul_f32_e32 v189, s9, v189
	v_pk_mul_f32 v[212:213], v[24:25], v[188:189] op_sel:[0,1]
	v_pk_mul_f32 v[214:215], v[26:27], v[188:189] op_sel:[0,1]
	v_pk_mul_f32 v[216:217], v[20:21], v[188:189] op_sel:[0,1]
	v_pk_mul_f32 v[218:219], v[22:23], v[188:189] op_sel:[0,1]
	ds_bpermute_b32 v228, v0, v212
	ds_bpermute_b32 v229, v0, v213
	ds_bpermute_b32 v230, v0, v214
	ds_bpermute_b32 v231, v0, v215
	ds_bpermute_b32 v132, v0, v216
	ds_bpermute_b32 v133, v0, v217
	ds_bpermute_b32 v134, v0, v218
	ds_bpermute_b32 v135, v0, v219
	s_waitcnt lgkmcnt(0)
	s_waitcnt vmcnt(1)
	v_pk_mul_f32 v[176:177], v[212:213], v[176:177]
	v_pk_mul_f32 v[178:179], v[214:215], v[178:179]
	v_pk_mul_f32 v[180:181], v[216:217], v[180:181]
	v_pk_mul_f32 v[182:183], v[218:219], v[182:183]
	v_pk_mul_f32 v[184:185], v[228:229], v[184:185]
	v_pk_mul_f32 v[186:187], v[230:231], v[186:187]
	v_pk_mul_f32 v[190:191], v[132:133], v[190:191]
	v_pk_mul_f32 v[192:193], v[134:135], v[192:193]
	s_mov_b64 exec, vcc
	v_pk_add_f32 v[212:213], v[176:177], v[184:185]
	v_pk_add_f32 v[214:215], v[178:179], v[186:187]
	v_pk_add_f32 v[216:217], v[180:181], v[190:191]
	v_pk_add_f32 v[218:219], v[182:183], v[192:193]
	s_mov_b64 exec, s[56:57]
	v_pk_add_f32 v[212:213], v[176:177], v[184:185] neg_lo:[0,1] neg_hi:[0,1]
	v_pk_add_f32 v[214:215], v[178:179], v[186:187] neg_lo:[0,1] neg_hi:[0,1]
	v_pk_add_f32 v[216:217], v[180:181], v[190:191] neg_lo:[0,1] neg_hi:[0,1]
	v_pk_add_f32 v[218:219], v[182:183], v[192:193] neg_lo:[0,1] neg_hi:[0,1]
	s_mov_b64 exec, s[100:101]
	v_cvt_pk_bf16_f32 v228, v212, v213
	v_cvt_pk_bf16_f32 v229, v214, v215
	v_cvt_pk_bf16_f32 v230, v216, v217
	v_cvt_pk_bf16_f32 v231, v218, v219
	v_lshl_add_u64 v[132:133], s[12:13], 1, v[142:143]
	global_store_dwordx4 v[132:133], v[228:231], off
